# v42 + SGU strip sections: bias reads kept in flight behind counted lgkmcnt waits instead of 16 serial LDS round trips
# speedup vs baseline: 1.0053x; 1.0053x over previous
.LBB0_629:
	s_and_saveexec_b64 s[6:7], s[2:3]
	ds_write_b64 v134, v[118:119]
	s_or_b64 exec, exec, s[6:7]
	s_add_i32 s19, s10, s96
	s_cmpk_lt_i32 s19, 0x840
	s_cselect_b64 s[6:7], -1, 0
	s_and_b64 s[0:1], s[6:7], exec
	s_cselect_b32 s0, s19, s10
	s_ashr_i32 s1, s0, 31
	s_lshr_b32 s1, s1, 28
	s_add_i32 s1, s0, s1
	s_and_b32 s8, s1, 0xfffff0
	s_sub_i32 s10, s0, s8
	s_lshl_b32 s0, s1, 3
	s_and_b32 s0, s0, 0xffffff80
	s_ashr_i32 s1, s0, 31
	s_lshl_b64 s[8:9], s[0:1], 13
	v_readlane_b32 s22, v252, 0
	v_readlane_b32 s23, v252, 1
	s_add_u32 s21, s22, s8
	s_addc_u32 s23, s23, s9
	s_lshl_b32 s10, s10, 8
	s_ashr_i32 s11, s10, 31
	s_lshl_b64 s[10:11], s[10:11], 1
	s_add_u32 s22, s21, s10
	s_addc_u32 s23, s23, s11
	s_add_u32 s24, s22, 0x20000
	ds_write_b128 v231, v[18:21]
	ds_write_b128 v232, v[22:25]
	ds_write_b128 v233, v[26:29]
	ds_write_b128 v238, v[30:33]
	ds_write_b128 v239, v[34:37]
	ds_write_b128 v240, v[38:41]
	ds_write_b128 v241, v[42:45]
	ds_write_b128 v242, v[46:49]
	s_waitcnt lgkmcnt(0)
	s_barrier
	s_nop 4
	global_load_dwordx4 v[18:21], v129, s[22:23] nt
	s_addc_u32 s25, s23, 0
	s_nop 4
	global_load_dwordx4 v[22:25], v129, s[24:25] nt
	s_add_u32 s24, s22, 0x40000
	s_addc_u32 s25, s23, 0
	s_nop 4
	global_load_dwordx4 v[26:29], v129, s[24:25] nt
	s_add_u32 s24, s22, 0x60000
	s_addc_u32 s25, s23, 0
	s_nop 4
	global_load_dwordx4 v[30:33], v129, s[24:25] nt
	s_add_u32 s24, s22, 0x80000
	s_addc_u32 s25, s23, 0
	s_nop 4
	global_load_dwordx4 v[34:37], v129, s[24:25] nt
	s_add_u32 s24, s22, 0xa0000
	s_addc_u32 s25, s23, 0
	s_nop 4
	global_load_dwordx4 v[38:41], v129, s[24:25] nt
	s_add_u32 s24, s22, 0xc0000
	s_addc_u32 s25, s23, 0
	s_add_u32 s22, s22, 0xe0000
	s_nop 4
	global_load_dwordx4 v[42:45], v129, s[24:25] nt
	s_addc_u32 s23, s23, 0
	s_lshl_b64 s[0:1], s[0:1], 3
	s_nop 4
	global_load_dwordx4 v[46:49], v129, s[22:23] nt
	s_add_u32 s0, s12, s0
	s_addc_u32 s1, s83, s1
	s_nop 4
	global_load_dwordx2 v[118:119], v131, s[0:1]
	v_add_u32_e32 v6, 16, v136
	ds_read_b32 v110, v135
	ds_read_b32 v112, v133 offset:1024
	ds_read_b128 v[2:5], v136
	ds_read_u16 v82, v243
	ds_read_u16 v86, v244
	ds_read_b128 v[6:9], v6
	ds_read_u16 v83, v244 offset:528
	ds_read_u16 v87, v244 offset:1056
	v_add_u32_e32 v10, 32, v136
	v_add_u32_e32 v14, 48, v136
	ds_read_b128 v[10:13], v10
	ds_read_u16 v88, v244 offset:1584
	ds_read_u16 v89, v244 offset:2112
	ds_read_b128 v[14:17], v14
	ds_read_u16 v90, v244 offset:2640
	ds_read_u16 v91, v245
	s_waitcnt lgkmcnt(0)
	v_lshlrev_b32_e32 v83, 16, v83
	v_lshlrev_b32_e32 v82, 16, v82
	v_mov_b32_e32 v84, v2
	v_mov_b32_e32 v85, v6
	v_pk_add_f32 v[82:83], v[82:83], v[84:85] neg_lo:[0,1] neg_hi:[0,1]
	v_mov_b32_e32 v6, v3
	v_pk_mul_f32 v[2:3], v[6:7], v[82:83]
	v_lshlrev_b32_e32 v7, 16, v87
	v_lshlrev_b32_e32 v6, 16, v86
	v_mov_b32_e32 v82, v4
	v_mov_b32_e32 v83, v8
	v_pk_add_f32 v[6:7], v[6:7], v[82:83] neg_lo:[0,1] neg_hi:[0,1]
	v_mov_b32_e32 v8, v5
	v_pk_mul_f32 v[4:5], v[8:9], v[6:7]
	v_lshlrev_b32_e32 v7, 16, v90
	v_lshlrev_b32_e32 v6, 16, v88
	v_mov_b32_e32 v8, v10
	v_mov_b32_e32 v9, v14
	v_pk_add_f32 v[6:7], v[6:7], v[8:9] neg_lo:[0,1] neg_hi:[0,1]
	v_mov_b32_e32 v14, v11
	v_lshlrev_b32_e32 v9, 16, v91
	v_lshlrev_b32_e32 v8, 16, v89
	v_mov_b32_e32 v10, v12
	v_mov_b32_e32 v11, v16
	v_pk_add_f32 v[8:9], v[8:9], v[10:11] neg_lo:[0,1] neg_hi:[0,1]
	v_mov_b32_e32 v16, v13
	v_pk_mul_f32 v[8:9], v[16:17], v[8:9]
	v_pk_fma_f32 v[4:5], v[110:111], v[4:5], v[112:113] op_sel_hi:[0,1,0]
	v_pk_mul_f32 v[6:7], v[14:15], v[6:7]
	v_pk_fma_f32 v[8:9], v[110:111], v[8:9], v[112:113] op_sel_hi:[0,1,0]
	v_pk_fma_f32 v[2:3], v[110:111], v[2:3], v[112:113] op_sel_hi:[0,1,0]
	v_pk_fma_f32 v[6:7], v[110:111], v[6:7], v[112:113] op_sel_hi:[0,1,0]
	v_bfe_u32 v10, v9, 16, 1
	v_bfe_u32 v12, v5, 16, 1
	v_bfe_u32 v11, v8, 16, 1
	v_bfe_u32 v13, v4, 16, 1
	v_add3_u32 v5, v5, v12, s53
	v_add3_u32 v9, v9, v10, s53
	v_bfe_u32 v10, v2, 16, 1
	v_bfe_u32 v12, v6, 16, 1
	v_add3_u32 v4, v4, v13, s53
	v_add3_u32 v8, v8, v11, s53
	v_bfe_u32 v11, v3, 16, 1
	v_bfe_u32 v13, v7, 16, 1
	v_add3_u32 v6, v6, v12, s53
	v_add3_u32 v2, v2, v10, s53
	v_add3_u32 v7, v7, v13, s53
	v_add3_u32 v3, v3, v11, s53
	v_lshrrev_b32_e32 v2, 16, v2
	v_lshrrev_b32_e32 v6, 16, v6
	v_lshrrev_b32_e32 v3, 16, v3
	v_lshrrev_b32_e32 v7, 16, v7
	v_and_or_b32 v84, v8, s77, v6
	v_and_or_b32 v82, v4, s77, v2
	v_add_u32_e32 v2, 0x80, v136
	v_add_u32_e32 v6, 0x90, v136
	v_and_or_b32 v85, v9, s77, v7
	v_and_or_b32 v83, v5, s77, v3
	ds_read_b128 v[2:5], v2
	ds_read_u16 v86, v245 offset:4752
	ds_read_u16 v90, v245 offset:5280
	ds_read_b128 v[6:9], v6
	ds_read_u16 v87, v245 offset:5808
	ds_read_u16 v91, v245 offset:6336
	v_add_u32_e32 v10, 0xa0, v136
	v_add_u32_e32 v14, 0xb0, v136
	ds_read_b128 v[10:13], v10
	ds_read_u16 v92, v245 offset:6864
	ds_read_u16 v93, v246
	ds_read_b128 v[14:17], v14
	ds_read_u16 v94, v246 offset:528
	ds_read_u16 v95, v246 offset:1056
	s_waitcnt lgkmcnt(0)
	v_lshlrev_b32_e32 v87, 16, v87
	v_lshlrev_b32_e32 v86, 16, v86
	v_mov_b32_e32 v88, v2
	v_mov_b32_e32 v89, v6
	v_pk_add_f32 v[86:87], v[86:87], v[88:89] neg_lo:[0,1] neg_hi:[0,1]
	v_mov_b32_e32 v6, v3
	v_pk_mul_f32 v[2:3], v[6:7], v[86:87]
	v_lshlrev_b32_e32 v7, 16, v91
	v_lshlrev_b32_e32 v6, 16, v90
	v_mov_b32_e32 v86, v4
	v_mov_b32_e32 v87, v8
	v_pk_add_f32 v[6:7], v[6:7], v[86:87] neg_lo:[0,1] neg_hi:[0,1]
	v_mov_b32_e32 v8, v5
	v_pk_mul_f32 v[4:5], v[8:9], v[6:7]
	v_lshlrev_b32_e32 v7, 16, v94
	v_lshlrev_b32_e32 v6, 16, v92
	v_mov_b32_e32 v8, v10
	v_mov_b32_e32 v9, v14
	v_pk_add_f32 v[6:7], v[6:7], v[8:9] neg_lo:[0,1] neg_hi:[0,1]
	v_mov_b32_e32 v14, v11
	v_lshlrev_b32_e32 v9, 16, v95
	v_lshlrev_b32_e32 v8, 16, v93
	v_mov_b32_e32 v10, v12
	v_mov_b32_e32 v11, v16
	v_pk_add_f32 v[8:9], v[8:9], v[10:11] neg_lo:[0,1] neg_hi:[0,1]
	v_mov_b32_e32 v16, v13
	v_pk_mul_f32 v[8:9], v[16:17], v[8:9]
	v_pk_fma_f32 v[4:5], v[110:111], v[4:5], v[112:113] op_sel_hi:[0,1,0]
	v_pk_mul_f32 v[6:7], v[14:15], v[6:7]
	v_pk_fma_f32 v[8:9], v[110:111], v[8:9], v[112:113] op_sel_hi:[0,1,0]
	v_pk_fma_f32 v[2:3], v[110:111], v[2:3], v[112:113] op_sel_hi:[0,1,0]
	v_pk_fma_f32 v[6:7], v[110:111], v[6:7], v[112:113] op_sel_hi:[0,1,0]
	v_bfe_u32 v10, v9, 16, 1
	v_bfe_u32 v12, v5, 16, 1
	v_bfe_u32 v11, v8, 16, 1
	v_bfe_u32 v13, v4, 16, 1
	v_add3_u32 v5, v5, v12, s53
	v_add3_u32 v9, v9, v10, s53
	v_bfe_u32 v10, v2, 16, 1
	v_bfe_u32 v12, v6, 16, 1
	v_add3_u32 v4, v4, v13, s53
	v_add3_u32 v8, v8, v11, s53
	v_bfe_u32 v11, v3, 16, 1
	v_bfe_u32 v13, v7, 16, 1
	v_add3_u32 v6, v6, v12, s53
	v_add3_u32 v2, v2, v10, s53
	v_add3_u32 v7, v7, v13, s53
	v_add3_u32 v3, v3, v11, s53
	v_lshrrev_b32_e32 v2, 16, v2
	v_lshrrev_b32_e32 v6, 16, v6
	v_lshrrev_b32_e32 v3, 16, v3
	v_lshrrev_b32_e32 v7, 16, v7
	v_and_or_b32 v88, v8, s77, v6
	v_and_or_b32 v86, v4, s77, v2
	v_add_u32_e32 v2, 0x100, v136
	v_add_u32_e32 v6, 0x110, v136
	v_and_or_b32 v89, v9, s77, v7
	v_and_or_b32 v87, v5, s77, v3
	ds_read_b128 v[2:5], v2
	ds_read_u16 v90, v246 offset:5808
	ds_read_u16 v94, v246 offset:6336
	ds_read_b128 v[6:9], v6
	ds_read_u16 v91, v246 offset:6864
	ds_read_u16 v95, v247
	v_add_u32_e32 v10, 0x120, v136
	v_add_u32_e32 v14, 0x130, v136
	ds_read_b128 v[10:13], v10
	ds_read_u16 v96, v247 offset:528
	ds_read_u16 v97, v247 offset:1056
	ds_read_b128 v[14:17], v14
	ds_read_u16 v98, v247 offset:1584
	ds_read_u16 v99, v247 offset:2112
	s_waitcnt lgkmcnt(0)
	v_lshlrev_b32_e32 v91, 16, v91
	v_lshlrev_b32_e32 v90, 16, v90
	v_mov_b32_e32 v92, v2
	v_mov_b32_e32 v93, v6
	v_pk_add_f32 v[90:91], v[90:91], v[92:93] neg_lo:[0,1] neg_hi:[0,1]
	v_mov_b32_e32 v6, v3
	v_pk_mul_f32 v[2:3], v[6:7], v[90:91]
	v_lshlrev_b32_e32 v7, 16, v95
	v_lshlrev_b32_e32 v6, 16, v94
	v_mov_b32_e32 v90, v4
	v_mov_b32_e32 v91, v8
	v_pk_add_f32 v[6:7], v[6:7], v[90:91] neg_lo:[0,1] neg_hi:[0,1]
	v_mov_b32_e32 v8, v5
	v_pk_mul_f32 v[4:5], v[8:9], v[6:7]
	v_lshlrev_b32_e32 v7, 16, v98
	v_lshlrev_b32_e32 v6, 16, v96
	v_mov_b32_e32 v8, v10
	v_mov_b32_e32 v9, v14
	v_pk_add_f32 v[6:7], v[6:7], v[8:9] neg_lo:[0,1] neg_hi:[0,1]
	v_mov_b32_e32 v14, v11
	v_lshlrev_b32_e32 v9, 16, v99
	v_lshlrev_b32_e32 v8, 16, v97
	v_mov_b32_e32 v10, v12
	v_mov_b32_e32 v11, v16
	v_pk_add_f32 v[8:9], v[8:9], v[10:11] neg_lo:[0,1] neg_hi:[0,1]
	v_mov_b32_e32 v16, v13
	v_pk_mul_f32 v[8:9], v[16:17], v[8:9]
	v_pk_fma_f32 v[4:5], v[110:111], v[4:5], v[112:113] op_sel_hi:[0,1,0]
	v_pk_mul_f32 v[6:7], v[14:15], v[6:7]
	v_pk_fma_f32 v[8:9], v[110:111], v[8:9], v[112:113] op_sel_hi:[0,1,0]
	v_pk_fma_f32 v[2:3], v[110:111], v[2:3], v[112:113] op_sel_hi:[0,1,0]
	v_pk_fma_f32 v[6:7], v[110:111], v[6:7], v[112:113] op_sel_hi:[0,1,0]
	v_bfe_u32 v10, v9, 16, 1
	v_bfe_u32 v11, v8, 16, 1
	v_bfe_u32 v12, v5, 16, 1
	v_bfe_u32 v13, v4, 16, 1
	v_add3_u32 v4, v4, v13, s53
	v_add3_u32 v5, v5, v12, s53
	v_add3_u32 v8, v8, v11, s53
	v_add3_u32 v9, v9, v10, s53
	v_bfe_u32 v10, v2, 16, 1
	v_bfe_u32 v11, v3, 16, 1
	v_bfe_u32 v12, v6, 16, 1
	v_bfe_u32 v13, v7, 16, 1
	v_add3_u32 v7, v7, v13, s53
	v_add3_u32 v6, v6, v12, s53
	v_add3_u32 v3, v3, v11, s53
	v_add3_u32 v2, v2, v10, s53
	v_lshrrev_b32_e32 v2, 16, v2
	v_lshrrev_b32_e32 v3, 16, v3
	v_lshrrev_b32_e32 v6, 16, v6
	v_lshrrev_b32_e32 v7, 16, v7
	v_and_or_b32 v93, v9, s77, v7
	v_and_or_b32 v92, v8, s77, v6
	v_and_or_b32 v91, v5, s77, v3
	v_and_or_b32 v90, v4, s77, v2
	ds_read_b128 v[2:5], v137
	ds_read_u16 v94, v247 offset:6864
	ds_read_u16 v98, v248
	ds_read_b128 v[6:9], v138
	ds_read_u16 v95, v248 offset:528
	ds_read_u16 v99, v248 offset:1056
	ds_read_b128 v[10:13], v139
	ds_read_u16 v100, v248 offset:1584
	ds_read_u16 v101, v248 offset:2112
	ds_read_b128 v[14:17], v140
	ds_read_u16 v102, v248 offset:2640
	ds_read_u16 v103, v248 offset:3168
	s_waitcnt lgkmcnt(0)
	v_lshlrev_b32_e32 v95, 16, v95
	v_lshlrev_b32_e32 v94, 16, v94
	v_mov_b32_e32 v96, v2
	v_mov_b32_e32 v97, v6
	v_pk_add_f32 v[94:95], v[94:95], v[96:97] neg_lo:[0,1] neg_hi:[0,1]
	v_mov_b32_e32 v6, v3
	v_pk_mul_f32 v[2:3], v[6:7], v[94:95]
	v_lshlrev_b32_e32 v7, 16, v99
	v_lshlrev_b32_e32 v6, 16, v98
	v_mov_b32_e32 v94, v4
	v_mov_b32_e32 v95, v8
	v_pk_add_f32 v[6:7], v[6:7], v[94:95] neg_lo:[0,1] neg_hi:[0,1]
	v_mov_b32_e32 v8, v5
	v_pk_mul_f32 v[4:5], v[8:9], v[6:7]
	v_lshlrev_b32_e32 v7, 16, v102
	v_lshlrev_b32_e32 v6, 16, v100
	v_mov_b32_e32 v8, v10
	v_mov_b32_e32 v9, v14
	v_pk_add_f32 v[6:7], v[6:7], v[8:9] neg_lo:[0,1] neg_hi:[0,1]
	v_mov_b32_e32 v14, v11
	v_lshlrev_b32_e32 v9, 16, v103
	v_lshlrev_b32_e32 v8, 16, v101
	v_mov_b32_e32 v10, v12
	v_mov_b32_e32 v11, v16
	v_pk_add_f32 v[8:9], v[8:9], v[10:11] neg_lo:[0,1] neg_hi:[0,1]
	v_mov_b32_e32 v16, v13
	v_pk_mul_f32 v[8:9], v[16:17], v[8:9]
	v_pk_fma_f32 v[4:5], v[110:111], v[4:5], v[112:113] op_sel_hi:[0,1,0]
	v_pk_mul_f32 v[6:7], v[14:15], v[6:7]
	v_pk_fma_f32 v[8:9], v[110:111], v[8:9], v[112:113] op_sel_hi:[0,1,0]
	v_pk_fma_f32 v[2:3], v[110:111], v[2:3], v[112:113] op_sel_hi:[0,1,0]
	v_pk_fma_f32 v[6:7], v[110:111], v[6:7], v[112:113] op_sel_hi:[0,1,0]
	v_bfe_u32 v10, v9, 16, 1
	v_bfe_u32 v11, v8, 16, 1
	v_bfe_u32 v12, v5, 16, 1
	v_bfe_u32 v13, v4, 16, 1
	v_add3_u32 v4, v4, v13, s53
	v_add3_u32 v5, v5, v12, s53
	v_add3_u32 v8, v8, v11, s53
	v_add3_u32 v9, v9, v10, s53
	v_bfe_u32 v10, v2, 16, 1
	v_bfe_u32 v11, v3, 16, 1
	v_bfe_u32 v12, v6, 16, 1
	v_bfe_u32 v13, v7, 16, 1
	v_add3_u32 v7, v7, v13, s53
	v_add3_u32 v6, v6, v12, s53
	v_add3_u32 v3, v3, v11, s53
	v_add3_u32 v2, v2, v10, s53
	v_lshrrev_b32_e32 v2, 16, v2
	v_lshrrev_b32_e32 v3, 16, v3
	v_lshrrev_b32_e32 v6, 16, v6
	v_lshrrev_b32_e32 v7, 16, v7
	v_and_or_b32 v97, v9, s77, v7
	v_and_or_b32 v96, v8, s77, v6
	v_and_or_b32 v95, v5, s77, v3
	v_and_or_b32 v94, v4, s77, v2
	ds_read_b128 v[2:5], v141
	ds_read_u16 v98, v248 offset:7920
	ds_read_u16 v102, v248 offset:8448
	ds_read_b128 v[6:9], v142
	ds_read_u16 v99, v248 offset:8976
	ds_read_u16 v103, v248 offset:9504
	ds_read_b128 v[10:13], v143
	ds_read_u16 v104, v248 offset:10032
	ds_read_u16 v105, v248 offset:10560
	ds_read_b128 v[14:17], v144
	ds_read_u16 v106, v248 offset:11088
	ds_read_u16 v107, v248 offset:11616
	s_waitcnt lgkmcnt(0)
	v_lshlrev_b32_e32 v99, 16, v99
	v_lshlrev_b32_e32 v98, 16, v98
	v_mov_b32_e32 v100, v2
	v_mov_b32_e32 v101, v6
	v_pk_add_f32 v[98:99], v[98:99], v[100:101] neg_lo:[0,1] neg_hi:[0,1]
	v_mov_b32_e32 v6, v3
	v_pk_mul_f32 v[2:3], v[6:7], v[98:99]
	v_lshlrev_b32_e32 v7, 16, v103
	v_lshlrev_b32_e32 v6, 16, v102
	v_mov_b32_e32 v98, v4
	v_mov_b32_e32 v99, v8
	v_pk_add_f32 v[6:7], v[6:7], v[98:99] neg_lo:[0,1] neg_hi:[0,1]
	v_mov_b32_e32 v8, v5
	v_pk_mul_f32 v[4:5], v[8:9], v[6:7]
	v_lshlrev_b32_e32 v7, 16, v106
	v_lshlrev_b32_e32 v6, 16, v104
	v_mov_b32_e32 v8, v10
	v_mov_b32_e32 v9, v14
	v_pk_add_f32 v[6:7], v[6:7], v[8:9] neg_lo:[0,1] neg_hi:[0,1]
	v_mov_b32_e32 v14, v11
	v_lshlrev_b32_e32 v9, 16, v107
	v_lshlrev_b32_e32 v8, 16, v105
	v_mov_b32_e32 v10, v12
	v_mov_b32_e32 v11, v16
	v_pk_add_f32 v[8:9], v[8:9], v[10:11] neg_lo:[0,1] neg_hi:[0,1]
	v_mov_b32_e32 v16, v13
	v_pk_mul_f32 v[8:9], v[16:17], v[8:9]
	v_pk_fma_f32 v[4:5], v[110:111], v[4:5], v[112:113] op_sel_hi:[0,1,0]
	v_pk_mul_f32 v[6:7], v[14:15], v[6:7]
	v_pk_fma_f32 v[8:9], v[110:111], v[8:9], v[112:113] op_sel_hi:[0,1,0]
	v_pk_fma_f32 v[2:3], v[110:111], v[2:3], v[112:113] op_sel_hi:[0,1,0]
	v_pk_fma_f32 v[6:7], v[110:111], v[6:7], v[112:113] op_sel_hi:[0,1,0]
	v_bfe_u32 v10, v9, 16, 1
	v_bfe_u32 v11, v8, 16, 1
	v_bfe_u32 v12, v5, 16, 1
	v_bfe_u32 v13, v4, 16, 1
	v_add3_u32 v4, v4, v13, s53
	v_add3_u32 v5, v5, v12, s53
	v_add3_u32 v8, v8, v11, s53
	v_add3_u32 v9, v9, v10, s53
	v_bfe_u32 v10, v2, 16, 1
	v_bfe_u32 v11, v3, 16, 1
	v_bfe_u32 v12, v6, 16, 1
	v_bfe_u32 v13, v7, 16, 1
	v_add3_u32 v7, v7, v13, s53
	v_add3_u32 v6, v6, v12, s53
	v_add3_u32 v3, v3, v11, s53
	v_add3_u32 v2, v2, v10, s53
	v_lshrrev_b32_e32 v2, 16, v2
	v_lshrrev_b32_e32 v3, 16, v3
	v_lshrrev_b32_e32 v6, 16, v6
	v_lshrrev_b32_e32 v7, 16, v7
	v_and_or_b32 v101, v9, s77, v7
	v_and_or_b32 v100, v8, s77, v6
	v_and_or_b32 v99, v5, s77, v3
	v_and_or_b32 v98, v4, s77, v2
	ds_read_b128 v[2:5], v145
	ds_read_u16 v102, v248 offset:16368
	ds_read_u16 v106, v248 offset:16896
	ds_read_b128 v[6:9], v146
	ds_read_u16 v103, v248 offset:17424
	ds_read_u16 v107, v248 offset:17952
	ds_read_b128 v[10:13], v147
	ds_read_u16 v108, v248 offset:18480
	ds_read_u16 v109, v248 offset:19008
	ds_read_b128 v[14:17], v148
	ds_read_u16 v111, v248 offset:19536
	ds_read_u16 v113, v248 offset:20064
	s_waitcnt lgkmcnt(0)
	v_lshlrev_b32_e32 v103, 16, v103
	v_lshlrev_b32_e32 v102, 16, v102
	v_mov_b32_e32 v104, v2
	v_mov_b32_e32 v105, v6
	v_pk_add_f32 v[102:103], v[102:103], v[104:105] neg_lo:[0,1] neg_hi:[0,1]
	v_mov_b32_e32 v6, v3
	v_pk_mul_f32 v[2:3], v[6:7], v[102:103]
	v_lshlrev_b32_e32 v7, 16, v107
	v_lshlrev_b32_e32 v6, 16, v106
	v_mov_b32_e32 v102, v4
	v_mov_b32_e32 v103, v8
	v_pk_add_f32 v[6:7], v[6:7], v[102:103] neg_lo:[0,1] neg_hi:[0,1]
	v_mov_b32_e32 v8, v5
	v_pk_mul_f32 v[4:5], v[8:9], v[6:7]
	v_lshlrev_b32_e32 v7, 16, v111
	v_lshlrev_b32_e32 v6, 16, v108
	v_mov_b32_e32 v8, v10
	v_mov_b32_e32 v9, v14
	v_pk_add_f32 v[6:7], v[6:7], v[8:9] neg_lo:[0,1] neg_hi:[0,1]
	v_mov_b32_e32 v14, v11
	v_lshlrev_b32_e32 v9, 16, v113
	v_lshlrev_b32_e32 v8, 16, v109
	v_mov_b32_e32 v10, v12
	v_mov_b32_e32 v11, v16
	v_pk_add_f32 v[8:9], v[8:9], v[10:11] neg_lo:[0,1] neg_hi:[0,1]
	v_mov_b32_e32 v16, v13
	v_pk_mul_f32 v[8:9], v[16:17], v[8:9]
	v_pk_fma_f32 v[4:5], v[110:111], v[4:5], v[112:113] op_sel_hi:[0,1,0]
	v_pk_mul_f32 v[6:7], v[14:15], v[6:7]
	v_pk_fma_f32 v[8:9], v[110:111], v[8:9], v[112:113] op_sel_hi:[0,1,0]
	v_pk_fma_f32 v[2:3], v[110:111], v[2:3], v[112:113] op_sel_hi:[0,1,0]
	v_pk_fma_f32 v[6:7], v[110:111], v[6:7], v[112:113] op_sel_hi:[0,1,0]
	v_bfe_u32 v10, v9, 16, 1
	v_bfe_u32 v11, v8, 16, 1
	v_bfe_u32 v12, v5, 16, 1
	v_bfe_u32 v13, v4, 16, 1
	v_add3_u32 v4, v4, v13, s53
	v_add3_u32 v5, v5, v12, s53
	v_add3_u32 v8, v8, v11, s53
	v_add3_u32 v9, v9, v10, s53
	v_bfe_u32 v10, v2, 16, 1
	v_bfe_u32 v11, v3, 16, 1
	v_bfe_u32 v12, v6, 16, 1
	v_bfe_u32 v13, v7, 16, 1
	v_add3_u32 v7, v7, v13, s53
	v_add3_u32 v6, v6, v12, s53
	v_add3_u32 v3, v3, v11, s53
	v_add3_u32 v2, v2, v10, s53
	v_lshrrev_b32_e32 v2, 16, v2
	v_lshrrev_b32_e32 v3, 16, v3
	v_lshrrev_b32_e32 v6, 16, v6
	v_lshrrev_b32_e32 v7, 16, v7
	v_and_or_b32 v105, v9, s77, v7
	v_and_or_b32 v104, v8, s77, v6
	v_and_or_b32 v103, v5, s77, v3
	v_and_or_b32 v102, v4, s77, v2
	ds_read_b128 v[2:5], v149
	ds_read_u16 v106, v248 offset:24816
	ds_read_u16 v111, v248 offset:25344
	ds_read_b128 v[6:9], v150
	ds_read_u16 v107, v248 offset:25872
	ds_read_u16 v113, v248 offset:26400
	ds_read_b128 v[10:13], v151
	ds_read_u16 v114, v248 offset:26928
	ds_read_u16 v115, v248 offset:27456
	ds_read_b128 v[14:17], v152
	ds_read_u16 v116, v248 offset:27984
	ds_read_u16 v117, v248 offset:28512
	s_waitcnt lgkmcnt(0)
	v_lshlrev_b32_e32 v107, 16, v107
	v_lshlrev_b32_e32 v106, 16, v106
	v_mov_b32_e32 v108, v2
	v_mov_b32_e32 v109, v6
	v_pk_add_f32 v[106:107], v[106:107], v[108:109] neg_lo:[0,1] neg_hi:[0,1]
	v_mov_b32_e32 v6, v3
	v_pk_mul_f32 v[2:3], v[6:7], v[106:107]
	v_lshlrev_b32_e32 v7, 16, v113
	v_lshlrev_b32_e32 v6, 16, v111
	v_mov_b32_e32 v106, v4
	v_mov_b32_e32 v107, v8
	v_pk_add_f32 v[6:7], v[6:7], v[106:107] neg_lo:[0,1] neg_hi:[0,1]
	v_mov_b32_e32 v8, v5
	v_pk_mul_f32 v[4:5], v[8:9], v[6:7]
	v_lshlrev_b32_e32 v7, 16, v116
	v_lshlrev_b32_e32 v6, 16, v114
	v_mov_b32_e32 v8, v10
	v_mov_b32_e32 v9, v14
	v_pk_add_f32 v[6:7], v[6:7], v[8:9] neg_lo:[0,1] neg_hi:[0,1]
	v_mov_b32_e32 v14, v11
	v_lshlrev_b32_e32 v9, 16, v117
	v_lshlrev_b32_e32 v8, 16, v115
	v_mov_b32_e32 v10, v12
	v_mov_b32_e32 v11, v16
	v_pk_add_f32 v[8:9], v[8:9], v[10:11] neg_lo:[0,1] neg_hi:[0,1]
	v_mov_b32_e32 v16, v13
	v_pk_mul_f32 v[8:9], v[16:17], v[8:9]
	v_pk_fma_f32 v[4:5], v[110:111], v[4:5], v[112:113] op_sel_hi:[0,1,0]
	v_pk_mul_f32 v[6:7], v[14:15], v[6:7]
	v_pk_fma_f32 v[8:9], v[110:111], v[8:9], v[112:113] op_sel_hi:[0,1,0]
	v_pk_fma_f32 v[2:3], v[110:111], v[2:3], v[112:113] op_sel_hi:[0,1,0]
	v_pk_fma_f32 v[6:7], v[110:111], v[6:7], v[112:113] op_sel_hi:[0,1,0]
	v_bfe_u32 v10, v9, 16, 1
	v_bfe_u32 v11, v8, 16, 1
	v_bfe_u32 v12, v5, 16, 1
	v_bfe_u32 v13, v4, 16, 1
	v_add3_u32 v4, v4, v13, s53
	v_add3_u32 v5, v5, v12, s53
	v_add3_u32 v8, v8, v11, s53
	v_add3_u32 v9, v9, v10, s53
	v_bfe_u32 v10, v2, 16, 1
	v_bfe_u32 v11, v3, 16, 1
	v_bfe_u32 v12, v6, 16, 1
	v_bfe_u32 v13, v7, 16, 1
	v_add3_u32 v7, v7, v13, s53
	v_add3_u32 v6, v6, v12, s53
	v_add3_u32 v3, v3, v11, s53
	v_add3_u32 v2, v2, v10, s53
	v_lshrrev_b32_e32 v2, 16, v2
	v_lshrrev_b32_e32 v3, 16, v3
	v_lshrrev_b32_e32 v6, 16, v6
	v_lshrrev_b32_e32 v7, 16, v7
	v_and_or_b32 v109, v9, s77, v7
	v_and_or_b32 v108, v8, s77, v6
	v_and_or_b32 v107, v5, s77, v3
	v_and_or_b32 v106, v4, s77, v2
	ds_read_b128 v[6:9], v153
	ds_read_u16 v114, v248 offset:33264
	ds_read_u16 v116, v248 offset:33792
	ds_read_b128 v[10:13], v154
	ds_read_u16 v115, v248 offset:34320
	ds_read_u16 v117, v248 offset:34848
	ds_read_b128 v[2:5], v155
	ds_read_u16 v113, v248 offset:35376
	ds_read_u16 v111, v248 offset:35904
	ds_read_b128 v[14:17], v156
	ds_read_u16 v235, v248 offset:36432
	s_waitcnt lgkmcnt(0)
	v_lshlrev_b32_e32 v115, 16, v115
	v_lshlrev_b32_e32 v114, 16, v114
	v_mov_b32_e32 v206, v6
	v_mov_b32_e32 v207, v10
	v_pk_add_f32 v[114:115], v[114:115], v[206:207] neg_lo:[0,1] neg_hi:[0,1]
	v_lshlrev_b32_e32 v117, 16, v117
	v_lshlrev_b32_e32 v116, 16, v116
	v_mov_b32_e32 v206, v8
	v_mov_b32_e32 v207, v12
	v_pk_add_f32 v[116:117], v[116:117], v[206:207] neg_lo:[0,1] neg_hi:[0,1]
	ds_read_u16 v206, v248 offset:36960
	v_mov_b32_e32 v10, v7
	v_mov_b32_e32 v12, v9
	v_pk_mul_f32 v[6:7], v[10:11], v[114:115]
	v_pk_mul_f32 v[8:9], v[12:13], v[116:117]
	v_lshlrev_b32_e32 v11, 16, v235
	v_lshlrev_b32_e32 v10, 16, v113
	v_mov_b32_e32 v12, v2
	v_mov_b32_e32 v13, v14
	v_pk_add_f32 v[10:11], v[10:11], v[12:13] neg_lo:[0,1] neg_hi:[0,1]
	v_mov_b32_e32 v14, v3
	v_pk_mul_f32 v[2:3], v[14:15], v[10:11]
	s_waitcnt lgkmcnt(0)
	v_lshlrev_b32_e32 v11, 16, v206
	v_lshlrev_b32_e32 v10, 16, v111
	v_mov_b32_e32 v12, v4
	v_mov_b32_e32 v13, v16
	v_pk_fma_f32 v[8:9], v[110:111], v[8:9], v[112:113] op_sel_hi:[0,1,0]
	v_pk_add_f32 v[10:11], v[10:11], v[12:13] neg_lo:[0,1] neg_hi:[0,1]
	v_mov_b32_e32 v16, v5
	v_pk_mul_f32 v[4:5], v[16:17], v[10:11]
	v_bfe_u32 v12, v9, 16, 1
	v_bfe_u32 v13, v8, 16, 1
	s_barrier
	s_waitcnt vmcnt(9)
	v_pk_fma_f32 v[6:7], v[110:111], v[6:7], v[112:113] op_sel_hi:[0,1,0]
	v_pk_fma_f32 v[2:3], v[110:111], v[2:3], v[112:113] op_sel_hi:[0,1,0]
	v_pk_fma_f32 v[4:5], v[110:111], v[4:5], v[112:113] op_sel_hi:[0,1,0]
	v_add3_u32 v110, v8, v13, s53
	v_add3_u32 v111, v9, v12, s53
	ds_read_b128 v[12:15], v249
	v_bfe_u32 v10, v5, 16, 1
	v_bfe_u32 v11, v4, 16, 1
	v_add3_u32 v4, v4, v11, s53
	v_add3_u32 v5, v5, v10, s53
	v_bfe_u32 v9, v7, 16, 1
	v_bfe_u32 v10, v2, 16, 1
	v_bfe_u32 v11, v3, 16, 1
	v_add3_u32 v3, v3, v11, s53
	v_add3_u32 v2, v2, v10, s53
	v_add3_u32 v206, v7, v9, s53
	v_bfe_u32 v8, v6, 16, 1
	v_lshrrev_b32_e32 v2, 16, v2
	v_lshrrev_b32_e32 v3, 16, v3
	ds_read_b128 v[114:117], v249 offset:32
	v_lshrrev_b32_e32 v206, 16, v206
	v_add3_u32 v207, v6, v8, s53
	v_and_or_b32 v113, v5, s77, v3
	v_and_or_b32 v112, v4, s77, v2
	v_and_or_b32 v111, v111, s77, v206
	ds_read_b32 v206, v157
	s_waitcnt lgkmcnt(0)
	v_mfma_f32_32x32x16_bf16 v[2:17], v[12:15], v[82:85], 0
	v_lshrrev_b32_e32 v207, 16, v207
	v_and_or_b32 v110, v110, s77, v207
	s_lshl_b32 s0, s20, 12
	s_sub_i32 s0, s17, s0
	s_ashr_i32 s1, s0, 31
	v_mfma_f32_32x32x16_bf16 v[2:17], v[114:117], v[86:89], v[2:17]
	ds_read_b128 v[114:117], v249 offset:64
	s_waitcnt lgkmcnt(0)
	v_mfma_f32_32x32x16_bf16 v[2:17], v[114:117], v[90:93], v[2:17]
	ds_read_b128 v[114:117], v249 offset:96
	s_waitcnt lgkmcnt(0)
	v_mfma_f32_32x32x16_bf16 v[2:17], v[114:117], v[94:97], v[2:17]
	ds_read_b128 v[114:117], v249 offset:128
	s_waitcnt lgkmcnt(0)
	v_mfma_f32_32x32x16_bf16 v[2:17], v[114:117], v[98:101], v[2:17]
	ds_read_b128 v[114:117], v249 offset:160
	s_waitcnt lgkmcnt(0)
	v_mfma_f32_32x32x16_bf16 v[2:17], v[114:117], v[102:105], v[2:17]
	ds_read_b128 v[114:117], v249 offset:192
	s_waitcnt lgkmcnt(0)
	v_mfma_f32_32x32x16_bf16 v[2:17], v[114:117], v[106:109], v[2:17]
	ds_read_b128 v[114:117], v249 offset:224
	s_waitcnt lgkmcnt(0)
	v_mfma_f32_32x32x16_bf16 v[2:17], v[114:117], v[110:113], v[2:17]
	ds_read_b32 v114, v158
	ds_read_b32 v115, v159
	ds_read_b32 v116, v160
	ds_read_b32 v117, v161
	s_nop 11
	v_add_f32_e32 v2, v2, v206
	ds_write_b32 v250, v2
	ds_read_b32 v206, v162
	s_waitcnt lgkmcnt(5)
	v_add_f32_e32 v114, v3, v114
	ds_write_b32 v204, v114
	ds_read_b32 v114, v163
	s_waitcnt lgkmcnt(6)
	v_add_f32_e32 v115, v4, v115
	ds_write_b32 v204, v115 offset:144
	ds_read_b32 v115, v164
	s_waitcnt lgkmcnt(7)
	v_add_f32_e32 v116, v5, v116
	ds_write_b32 v204, v116 offset:288
	ds_read_b32 v116, v165
	s_waitcnt lgkmcnt(8)
	v_add_f32_e32 v117, v6, v117
	ds_write_b32 v204, v117 offset:1008
	ds_read_b32 v117, v166
	s_waitcnt lgkmcnt(8)
	v_add_f32_e32 v206, v7, v206
	ds_write_b32 v204, v206 offset:1152
	ds_read_b32 v206, v167
	s_waitcnt lgkmcnt(8)
	v_add_f32_e32 v114, v8, v114
	ds_write_b32 v204, v114 offset:1296
	ds_read_b32 v114, v168
	s_waitcnt lgkmcnt(8)
	v_add_f32_e32 v115, v9, v115
	ds_write_b32 v204, v115 offset:1440
	ds_read_b32 v115, v169
	s_waitcnt lgkmcnt(8)
	v_add_f32_e32 v116, v10, v116
	ds_write_b32 v204, v116 offset:2160
	ds_read_b32 v116, v170
	s_waitcnt lgkmcnt(8)
	v_add_f32_e32 v117, v11, v117
	ds_write_b32 v204, v117 offset:2304
	ds_read_b32 v117, v171
	s_waitcnt lgkmcnt(8)
	v_add_f32_e32 v206, v12, v206
	ds_write_b32 v204, v206 offset:2448
	ds_read_b32 v206, v172
	s_waitcnt lgkmcnt(8)
	v_add_f32_e32 v114, v13, v114
	ds_write_b32 v204, v114 offset:2592
	s_waitcnt lgkmcnt(7)
	v_add_f32_e32 v115, v14, v115
	ds_write_b32 v204, v115 offset:3312
	s_waitcnt lgkmcnt(6)
	v_add_f32_e32 v116, v15, v116
	ds_write_b32 v204, v116 offset:3456
	s_waitcnt lgkmcnt(5)
	v_add_f32_e32 v117, v16, v117
	ds_write_b32 v204, v117 offset:3600
	s_waitcnt lgkmcnt(4)
	v_add_f32_e32 v206, v17, v206
	ds_write_b32 v204, v206 offset:3744
	ds_read_b128 v[2:5], v249 offset:8704
	ds_read_b128 v[114:117], v249 offset:8736
	s_waitcnt lgkmcnt(0)
	v_mfma_f32_32x32x16_bf16 v[2:17], v[2:5], v[82:85], 0
	v_mfma_f32_32x32x16_bf16 v[2:17], v[114:117], v[86:89], v[2:17]
	ds_read_b128 v[114:117], v249 offset:8768
	s_waitcnt lgkmcnt(0)
	v_mfma_f32_32x32x16_bf16 v[2:17], v[114:117], v[90:93], v[2:17]
	ds_read_b128 v[114:117], v249 offset:8800
	s_waitcnt lgkmcnt(0)
	v_mfma_f32_32x32x16_bf16 v[2:17], v[114:117], v[94:97], v[2:17]
	ds_read_b128 v[114:117], v249 offset:8832
	s_waitcnt lgkmcnt(0)
	v_mfma_f32_32x32x16_bf16 v[2:17], v[114:117], v[98:101], v[2:17]
	ds_read_b128 v[114:117], v249 offset:8864
	s_waitcnt lgkmcnt(0)
	v_mfma_f32_32x32x16_bf16 v[2:17], v[114:117], v[102:105], v[2:17]
	ds_read_b128 v[114:117], v249 offset:8896
	s_waitcnt lgkmcnt(0)
	v_mfma_f32_32x32x16_bf16 v[2:17], v[114:117], v[106:109], v[2:17]
	ds_read_b128 v[114:117], v249 offset:8928
	ds_read_b32 v206, v173
	s_waitcnt lgkmcnt(0)
	v_mfma_f32_32x32x16_bf16 v[2:17], v[114:117], v[110:113], v[2:17]
	ds_read_b32 v114, v174
	ds_read_b32 v115, v175
	ds_read_b32 v116, v176
	ds_read_b32 v117, v177
	s_nop 11
	v_add_f32_e32 v2, v2, v206
	ds_write_b32 v204, v2 offset:4464
	ds_read_b32 v206, v178
	s_waitcnt lgkmcnt(5)
	v_add_f32_e32 v114, v3, v114
	ds_write_b32 v204, v114 offset:4608
	ds_read_b32 v114, v179
	s_waitcnt lgkmcnt(6)
	v_add_f32_e32 v115, v4, v115
	ds_write_b32 v204, v115 offset:4752
	ds_read_b32 v115, v180
	s_waitcnt lgkmcnt(7)
	v_add_f32_e32 v116, v5, v116
	ds_write_b32 v204, v116 offset:4896
	ds_read_b32 v116, v181
	s_waitcnt lgkmcnt(8)
	v_add_f32_e32 v117, v6, v117
	ds_write_b32 v204, v117 offset:5616
	ds_read_b32 v117, v182
	s_waitcnt lgkmcnt(8)
	v_add_f32_e32 v206, v7, v206
	ds_write_b32 v204, v206 offset:5760
	ds_read_b32 v206, v183
	s_waitcnt lgkmcnt(8)
	v_add_f32_e32 v114, v8, v114
	ds_write_b32 v204, v114 offset:5904
	ds_read_b32 v114, v184
	s_waitcnt lgkmcnt(8)
	v_add_f32_e32 v115, v9, v115
	ds_write_b32 v204, v115 offset:6048
	ds_read_b32 v115, v185
	s_waitcnt lgkmcnt(8)
	v_add_f32_e32 v116, v10, v116
	ds_write_b32 v204, v116 offset:6768
	ds_read_b32 v116, v186
	v_lshlrev_b32_e32 v10, 16, v78
	s_waitcnt lgkmcnt(8)
	v_add_f32_e32 v117, v11, v117
	ds_write_b32 v204, v117 offset:6912
	ds_read_b32 v117, v187
	v_lshlrev_b32_e32 v11, 16, v79
	s_waitcnt lgkmcnt(8)
	v_add_f32_e32 v206, v12, v206
	ds_write_b32 v204, v206 offset:7056
	ds_read_b32 v206, v188
	s_waitcnt lgkmcnt(8)
	v_add_f32_e32 v114, v13, v114
	ds_write_b32 v204, v114 offset:7200
	s_waitcnt lgkmcnt(7)
	v_add_f32_e32 v115, v14, v115
	ds_write_b32 v204, v115 offset:7920
	v_lshl_or_b32 v2, s20, 7, v128
	s_waitcnt lgkmcnt(6)
	v_add_f32_e32 v116, v15, v116
	ds_write_b32 v204, v116 offset:8064
	v_ashrrev_i32_e32 v3, 31, v2
	v_lshlrev_b64 v[2:3], 13, v[2:3]
	v_lshl_add_u64 v[2:3], s[78:79], 0, v[2:3]
	v_lshl_add_u64 v[2:3], s[0:1], 1, v[2:3]
	s_waitcnt lgkmcnt(5)
	v_add_f32_e32 v117, v16, v117
	ds_write_b32 v204, v117 offset:8208
	v_lshl_add_u64 v[6:7], s[4:5], 1, v[2:3]
	v_lshl_add_u64 v[114:115], v[6:7], 0, v[202:203]
	s_mov_b32 s0, 0x60000
	s_waitcnt lgkmcnt(4)
	v_add_f32_e32 v206, v17, v206
	ds_write_b32 v204, v206 offset:8352
	s_waitcnt lgkmcnt(0)
	ds_read_b128 v[2:5], v205
	ds_read_b128 v[6:9], v205 offset:16
	s_waitcnt lgkmcnt(0)
	v_mov_b32_e32 v12, v2
	v_mov_b32_e32 v13, v4
	v_pk_mul_f32 v[10:11], v[12:13], v[10:11]
	v_and_b32_e32 v13, 0xffff0000, v79
	v_and_b32_e32 v12, 0xffff0000, v78
	v_mov_b32_e32 v4, v3
	v_pk_mul_f32 v[2:3], v[4:5], v[12:13]
	v_lshlrev_b32_e32 v5, 16, v81
	v_lshlrev_b32_e32 v4, 16, v80
	v_mov_b32_e32 v12, v6
	v_mov_b32_e32 v13, v8
	v_pk_mul_f32 v[4:5], v[12:13], v[4:5]
	v_and_b32_e32 v13, 0xffff0000, v81
	v_and_b32_e32 v12, 0xffff0000, v80
	v_mov_b32_e32 v8, v7
	v_pk_mul_f32 v[6:7], v[8:9], v[12:13]
	v_bfe_u32 v12, v3, 16, 1
	v_bfe_u32 v8, v7, 16, 1
	v_bfe_u32 v9, v6, 16, 1
	v_bfe_u32 v13, v2, 16, 1
	v_add3_u32 v2, v2, v13, s53
	v_add3_u32 v3, v3, v12, s53
	v_add3_u32 v6, v6, v9, s53
	v_add3_u32 v7, v7, v8, s53
	v_bfe_u32 v8, v10, 16, 1
	v_bfe_u32 v9, v11, 16, 1
	v_bfe_u32 v12, v4, 16, 1
	v_bfe_u32 v13, v5, 16, 1
	v_add3_u32 v5, v5, v13, s53
	v_add3_u32 v4, v4, v12, s53
	v_add3_u32 v9, v11, v9, s53
	v_add3_u32 v8, v10, v8, s53
	v_lshrrev_b32_e32 v8, 16, v8
	v_lshrrev_b32_e32 v9, 16, v9
	v_lshrrev_b32_e32 v4, 16, v4
	v_lshrrev_b32_e32 v5, 16, v5
	v_and_or_b32 v5, v7, s77, v5
	v_and_or_b32 v4, v6, s77, v4
	v_and_or_b32 v3, v3, s77, v9
	v_and_or_b32 v2, v2, s77, v8
	ds_read_b128 v[6:9], v205 offset:2304
	global_store_dwordx4 v[114:115], v[2:5], off
	ds_read_b128 v[2:5], v205 offset:2320
	v_lshlrev_b32_e32 v11, 16, v75
	v_lshlrev_b32_e32 v10, 16, v74
	s_waitcnt lgkmcnt(0)
	v_mov_b32_e32 v12, v6
	v_mov_b32_e32 v13, v8
	v_pk_mul_f32 v[10:11], v[12:13], v[10:11]
	v_and_b32_e32 v13, 0xffff0000, v75
	v_and_b32_e32 v12, 0xffff0000, v74
	v_mov_b32_e32 v8, v7
	v_pk_mul_f32 v[6:7], v[8:9], v[12:13]
	v_lshlrev_b32_e32 v9, 16, v77
	v_lshlrev_b32_e32 v8, 16, v76
	v_mov_b32_e32 v12, v2
	v_mov_b32_e32 v13, v4
	v_pk_mul_f32 v[8:9], v[12:13], v[8:9]
	v_and_b32_e32 v13, 0xffff0000, v77
	v_and_b32_e32 v12, 0xffff0000, v76
	v_mov_b32_e32 v4, v3
	v_pk_mul_f32 v[2:3], v[4:5], v[12:13]
	v_bfe_u32 v12, v7, 16, 1
	v_bfe_u32 v4, v3, 16, 1
	v_bfe_u32 v5, v2, 16, 1
	v_bfe_u32 v13, v6, 16, 1
	v_add3_u32 v6, v6, v13, s53
	v_add3_u32 v7, v7, v12, s53
	v_add3_u32 v2, v2, v5, s53
	v_add3_u32 v3, v3, v4, s53
	v_bfe_u32 v4, v10, 16, 1
	v_bfe_u32 v5, v11, 16, 1
	v_bfe_u32 v12, v8, 16, 1
	v_bfe_u32 v13, v9, 16, 1
	v_add3_u32 v9, v9, v13, s53
	v_add3_u32 v8, v8, v12, s53
	v_add3_u32 v5, v11, v5, s53
	v_add3_u32 v4, v10, v4, s53
	v_lshrrev_b32_e32 v10, 16, v4
	v_lshrrev_b32_e32 v11, 16, v5
	v_lshrrev_b32_e32 v4, 16, v8
	v_lshrrev_b32_e32 v5, 16, v9
	v_and_or_b32 v5, v3, s77, v5
	v_and_or_b32 v4, v2, s77, v4
	v_and_or_b32 v3, v7, s77, v11
	v_and_or_b32 v2, v6, s77, v10
	v_add_co_u32_e32 v10, vcc, s57, v114
	ds_read_b128 v[6:9], v205 offset:4608
	s_nop 0
	v_addc_co_u32_e32 v11, vcc, 0, v115, vcc
	global_store_dwordx4 v[10:11], v[2:5], off
	ds_read_b128 v[2:5], v205 offset:4624
	v_lshlrev_b32_e32 v11, 16, v71
	v_lshlrev_b32_e32 v10, 16, v70
	s_waitcnt lgkmcnt(0)
	v_mov_b32_e32 v12, v6
	v_mov_b32_e32 v13, v8
	v_pk_mul_f32 v[10:11], v[12:13], v[10:11]
	v_and_b32_e32 v13, 0xffff0000, v71
	v_and_b32_e32 v12, 0xffff0000, v70
	v_mov_b32_e32 v8, v7
	v_pk_mul_f32 v[6:7], v[8:9], v[12:13]
	v_lshlrev_b32_e32 v9, 16, v73
	v_lshlrev_b32_e32 v8, 16, v72
	v_mov_b32_e32 v12, v2
	v_mov_b32_e32 v13, v4
	v_pk_mul_f32 v[8:9], v[12:13], v[8:9]
	v_and_b32_e32 v13, 0xffff0000, v73
	v_and_b32_e32 v12, 0xffff0000, v72
	v_mov_b32_e32 v4, v3
	v_pk_mul_f32 v[2:3], v[4:5], v[12:13]
	v_bfe_u32 v12, v7, 16, 1
	v_bfe_u32 v4, v3, 16, 1
	v_bfe_u32 v5, v2, 16, 1
	v_bfe_u32 v13, v6, 16, 1
	v_add3_u32 v6, v6, v13, s53
	v_add3_u32 v7, v7, v12, s53
	v_add3_u32 v2, v2, v5, s53
	v_add3_u32 v3, v3, v4, s53
	v_bfe_u32 v4, v10, 16, 1
	v_bfe_u32 v5, v11, 16, 1
	v_bfe_u32 v12, v8, 16, 1
	v_bfe_u32 v13, v9, 16, 1
	v_add3_u32 v9, v9, v13, s53
	v_add3_u32 v8, v8, v12, s53
	v_add3_u32 v5, v11, v5, s53
	v_add3_u32 v4, v10, v4, s53
	v_lshrrev_b32_e32 v10, 16, v4
	v_lshrrev_b32_e32 v11, 16, v5
	v_lshrrev_b32_e32 v4, 16, v8
	v_lshrrev_b32_e32 v5, 16, v9
	v_and_or_b32 v5, v3, s77, v5
	v_and_or_b32 v4, v2, s77, v4
	v_and_or_b32 v3, v7, s77, v11
	v_and_or_b32 v2, v6, s77, v10
	v_add_co_u32_e32 v10, vcc, s88, v114
	ds_read_b128 v[6:9], v205 offset:6912
	s_nop 0
	v_addc_co_u32_e32 v11, vcc, 0, v115, vcc
	global_store_dwordx4 v[10:11], v[2:5], off
	ds_read_b128 v[2:5], v205 offset:6928
	v_lshlrev_b32_e32 v11, 16, v67
	v_lshlrev_b32_e32 v10, 16, v66
	s_waitcnt lgkmcnt(0)
	v_mov_b32_e32 v12, v6
	v_mov_b32_e32 v13, v8
	v_pk_mul_f32 v[10:11], v[12:13], v[10:11]
	v_and_b32_e32 v13, 0xffff0000, v67
	v_and_b32_e32 v12, 0xffff0000, v66
	v_mov_b32_e32 v8, v7
	v_pk_mul_f32 v[6:7], v[8:9], v[12:13]
	v_lshlrev_b32_e32 v9, 16, v69
	v_lshlrev_b32_e32 v8, 16, v68
	v_mov_b32_e32 v12, v2
	v_mov_b32_e32 v13, v4
	v_pk_mul_f32 v[8:9], v[12:13], v[8:9]
	v_and_b32_e32 v13, 0xffff0000, v69
	v_and_b32_e32 v12, 0xffff0000, v68
	v_mov_b32_e32 v4, v3
	v_pk_mul_f32 v[2:3], v[4:5], v[12:13]
	v_bfe_u32 v12, v7, 16, 1
	v_bfe_u32 v4, v3, 16, 1
	v_bfe_u32 v5, v2, 16, 1
	v_bfe_u32 v13, v6, 16, 1
	v_add3_u32 v7, v7, v12, s53
	v_add3_u32 v3, v3, v4, s53
	v_bfe_u32 v4, v10, 16, 1
	v_bfe_u32 v12, v8, 16, 1
	v_add3_u32 v6, v6, v13, s53
	v_add3_u32 v2, v2, v5, s53
	v_bfe_u32 v5, v11, 16, 1
	v_bfe_u32 v13, v9, 16, 1
	v_add3_u32 v8, v8, v12, s53
	v_add3_u32 v4, v10, v4, s53
	v_add3_u32 v9, v9, v13, s53
	v_add3_u32 v5, v11, v5, s53
	v_lshrrev_b32_e32 v10, 16, v4
	v_lshrrev_b32_e32 v4, 16, v8
	v_lshrrev_b32_e32 v11, 16, v5
	v_lshrrev_b32_e32 v5, 16, v9
	v_and_or_b32 v4, v2, s77, v4
	v_and_or_b32 v2, v6, s77, v10
	v_add_co_u32_e32 v6, vcc, s0, v114
	v_and_or_b32 v5, v3, s77, v5
	v_and_or_b32 v3, v7, s77, v11
	v_addc_co_u32_e32 v7, vcc, 0, v115, vcc
	global_store_dwordx4 v[6:7], v[2:5], off
	s_waitcnt lgkmcnt(0)
	ds_read_b128 v[2:5], v249 offset:17408
	ds_read_b128 v[66:69], v249 offset:17440
	s_waitcnt lgkmcnt(0)
	v_mfma_f32_32x32x16_bf16 v[2:17], v[2:5], v[82:85], 0
	s_mov_b32 s0, 0x80000
	v_mfma_f32_32x32x16_bf16 v[2:17], v[66:69], v[86:89], v[2:17]
	ds_read_b128 v[66:69], v249 offset:17472
	s_waitcnt lgkmcnt(0)
	v_mfma_f32_32x32x16_bf16 v[2:17], v[66:69], v[90:93], v[2:17]
	ds_read_b128 v[66:69], v249 offset:17504
	s_waitcnt lgkmcnt(0)
	v_mfma_f32_32x32x16_bf16 v[2:17], v[66:69], v[94:97], v[2:17]
	ds_read_b128 v[66:69], v249 offset:17536
	s_waitcnt lgkmcnt(0)
	v_mfma_f32_32x32x16_bf16 v[2:17], v[66:69], v[98:101], v[2:17]
	ds_read_b128 v[66:69], v249 offset:17568
	s_waitcnt lgkmcnt(0)
	v_mfma_f32_32x32x16_bf16 v[2:17], v[66:69], v[102:105], v[2:17]
	ds_read_b128 v[66:69], v249 offset:17600
	s_waitcnt lgkmcnt(0)
	v_mfma_f32_32x32x16_bf16 v[2:17], v[66:69], v[106:109], v[2:17]
	ds_read_b128 v[66:69], v249 offset:17632
	ds_read_b32 v70, v189
	s_waitcnt lgkmcnt(0)
	v_mfma_f32_32x32x16_bf16 v[2:17], v[66:69], v[110:113], v[2:17]
	ds_read_b32 v66, v190
	ds_read_b32 v67, v191
	ds_read_b32 v68, v192
	ds_read_b32 v69, v193
	ds_read_b32 v71, v194
	ds_read_b32 v72, v195
	s_nop 11
	v_add_f32_e32 v2, v2, v70
	ds_write_b32 v250, v2
	ds_read_b32 v70, v196
	s_waitcnt lgkmcnt(7)
	v_add_f32_e32 v66, v3, v66
	ds_write_b32 v204, v66
	ds_read_b32 v66, v197
	s_waitcnt lgkmcnt(8)
	v_add_f32_e32 v67, v4, v67
	ds_write_b32 v204, v67 offset:144
	ds_read_b32 v67, v198
	s_waitcnt lgkmcnt(9)
	v_add_f32_e32 v68, v5, v68
	ds_write_b32 v204, v68 offset:288
	ds_read_b32 v68, v199
	s_waitcnt lgkmcnt(10)
	v_add_f32_e32 v69, v6, v69
	ds_write_b32 v204, v69 offset:1008
	ds_read_b32 v69, v200
	s_waitcnt lgkmcnt(11)
	v_add_f32_e32 v71, v7, v71
	ds_write_b32 v204, v71 offset:1152
	ds_read_b32 v71, v201
	s_waitcnt lgkmcnt(12)
	v_add_f32_e32 v72, v8, v72
	ds_write_b32 v204, v72 offset:1296
	ds_read_b32 v72, v208
	s_waitcnt lgkmcnt(12)
	v_add_f32_e32 v70, v9, v70
	ds_write_b32 v204, v70 offset:1440
	ds_read_b32 v70, v209
	s_waitcnt lgkmcnt(12)
	v_add_f32_e32 v66, v10, v66
	ds_write_b32 v204, v66 offset:2160
	ds_read_b32 v66, v210
	s_waitcnt lgkmcnt(12)
	v_add_f32_e32 v67, v11, v67
	ds_write_b32 v204, v67 offset:2304
	s_waitcnt lgkmcnt(11)
	v_add_f32_e32 v68, v12, v68
	ds_write_b32 v204, v68 offset:2448
	s_waitcnt lgkmcnt(10)
	v_add_f32_e32 v69, v13, v69
	ds_write_b32 v204, v69 offset:2592
	s_waitcnt lgkmcnt(9)
	v_add_f32_e32 v71, v14, v71
	ds_write_b32 v204, v71 offset:3312
	s_waitcnt lgkmcnt(8)
	v_add_f32_e32 v72, v15, v72
	ds_write_b32 v204, v72 offset:3456
	s_waitcnt lgkmcnt(7)
	v_add_f32_e32 v70, v16, v70
	ds_write_b32 v204, v70 offset:3600
	s_waitcnt lgkmcnt(6)
	v_add_f32_e32 v66, v17, v66
	ds_write_b32 v204, v66 offset:3744
	ds_read_b128 v[2:5], v249 offset:26112
	ds_read_b128 v[66:69], v249 offset:26144
	s_waitcnt lgkmcnt(0)
	v_mfma_f32_32x32x16_bf16 v[2:17], v[2:5], v[82:85], 0
	v_mfma_f32_32x32x16_bf16 v[2:17], v[66:69], v[86:89], v[2:17]
	ds_read_b128 v[66:69], v249 offset:26176
	s_waitcnt lgkmcnt(0)
	v_mfma_f32_32x32x16_bf16 v[2:17], v[66:69], v[90:93], v[2:17]
	ds_read_b128 v[66:69], v249 offset:26208
	s_waitcnt lgkmcnt(0)
	v_mfma_f32_32x32x16_bf16 v[2:17], v[66:69], v[94:97], v[2:17]
	ds_read_b128 v[66:69], v249 offset:26240
	s_waitcnt lgkmcnt(0)
	v_mfma_f32_32x32x16_bf16 v[2:17], v[66:69], v[98:101], v[2:17]
	ds_read_b128 v[66:69], v249 offset:26272
	s_waitcnt lgkmcnt(0)
	v_mfma_f32_32x32x16_bf16 v[2:17], v[66:69], v[102:105], v[2:17]
	ds_read_b128 v[66:69], v249 offset:26304
	s_waitcnt lgkmcnt(0)
	v_mfma_f32_32x32x16_bf16 v[2:17], v[66:69], v[106:109], v[2:17]
	ds_read_b128 v[66:69], v249 offset:26336
	ds_read_b32 v70, v211
	s_waitcnt lgkmcnt(0)
	v_mfma_f32_32x32x16_bf16 v[2:17], v[66:69], v[110:113], v[2:17]
	ds_read_b32 v66, v212
	ds_read_b32 v67, v213
	ds_read_b32 v68, v214
	ds_read_b32 v69, v215
	ds_read_b32 v71, v216
	ds_read_b32 v72, v217
	s_nop 11
	v_add_f32_e32 v2, v2, v70
	ds_write_b32 v204, v2 offset:4464
	ds_read_b32 v70, v218
	s_waitcnt lgkmcnt(7)
	v_add_f32_e32 v66, v3, v66
	ds_write_b32 v204, v66 offset:4608
	ds_read_b32 v66, v219
	s_waitcnt lgkmcnt(8)
	v_add_f32_e32 v67, v4, v67
	ds_write_b32 v204, v67 offset:4752
	ds_read_b32 v67, v220
	s_waitcnt lgkmcnt(9)
	v_add_f32_e32 v68, v5, v68
	ds_write_b32 v204, v68 offset:4896
	ds_read_b32 v68, v221
	s_waitcnt lgkmcnt(10)
	v_add_f32_e32 v69, v6, v69
	ds_write_b32 v204, v69 offset:5616
	ds_read_b32 v69, v222
	s_waitcnt lgkmcnt(11)
	v_add_f32_e32 v71, v7, v71
	ds_write_b32 v204, v71 offset:5760
	ds_read_b32 v71, v223
	s_waitcnt lgkmcnt(12)
	v_add_f32_e32 v72, v8, v72
	ds_write_b32 v204, v72 offset:5904
	ds_read_b32 v72, v224
	s_waitcnt lgkmcnt(12)
	v_add_f32_e32 v70, v9, v70
	ds_write_b32 v204, v70 offset:6048
	ds_read_b32 v70, v225
	s_waitcnt lgkmcnt(12)
	v_add_f32_e32 v66, v10, v66
	ds_write_b32 v204, v66 offset:6768
	ds_read_b32 v66, v226
	v_lshlrev_b32_e32 v10, 16, v62
	s_waitcnt lgkmcnt(12)
	v_add_f32_e32 v67, v11, v67
	ds_write_b32 v204, v67 offset:6912
	v_lshlrev_b32_e32 v11, 16, v63
	s_waitcnt lgkmcnt(11)
	v_add_f32_e32 v68, v12, v68
	ds_write_b32 v204, v68 offset:7056
	s_waitcnt lgkmcnt(10)
	v_add_f32_e32 v69, v13, v69
	ds_write_b32 v204, v69 offset:7200
	s_waitcnt lgkmcnt(9)
	v_add_f32_e32 v71, v14, v71
	ds_write_b32 v204, v71 offset:7920
	s_waitcnt lgkmcnt(8)
	v_add_f32_e32 v72, v15, v72
	ds_write_b32 v204, v72 offset:8064
	s_waitcnt lgkmcnt(7)
	v_add_f32_e32 v70, v16, v70
	ds_write_b32 v204, v70 offset:8208
	s_waitcnt lgkmcnt(6)
	v_add_f32_e32 v66, v17, v66
	ds_write_b32 v204, v66 offset:8352
	s_waitcnt lgkmcnt(0)
	ds_read_b128 v[2:5], v205
	ds_read_b128 v[6:9], v205 offset:16
	s_waitcnt lgkmcnt(0)
	v_mov_b32_e32 v12, v2
	v_mov_b32_e32 v13, v4
	v_pk_mul_f32 v[10:11], v[12:13], v[10:11]
	v_and_b32_e32 v13, 0xffff0000, v63
	v_and_b32_e32 v12, 0xffff0000, v62
	v_mov_b32_e32 v4, v3
	v_pk_mul_f32 v[2:3], v[4:5], v[12:13]
	v_lshlrev_b32_e32 v5, 16, v65
	v_lshlrev_b32_e32 v4, 16, v64
	v_mov_b32_e32 v12, v6
	v_mov_b32_e32 v13, v8
	v_pk_mul_f32 v[4:5], v[12:13], v[4:5]
	v_and_b32_e32 v13, 0xffff0000, v65
	v_and_b32_e32 v12, 0xffff0000, v64
	v_mov_b32_e32 v8, v7
	v_pk_mul_f32 v[6:7], v[8:9], v[12:13]
	v_bfe_u32 v12, v3, 16, 1
	v_bfe_u32 v8, v7, 16, 1
	v_bfe_u32 v9, v6, 16, 1
	v_bfe_u32 v13, v2, 16, 1
	v_add3_u32 v2, v2, v13, s53
	v_add3_u32 v3, v3, v12, s53
	v_add3_u32 v6, v6, v9, s53
	v_add3_u32 v7, v7, v8, s53
	v_bfe_u32 v8, v10, 16, 1
	v_bfe_u32 v9, v11, 16, 1
	v_bfe_u32 v12, v4, 16, 1
	v_bfe_u32 v13, v5, 16, 1
	v_add3_u32 v5, v5, v13, s53
	v_add3_u32 v4, v4, v12, s53
	v_add3_u32 v9, v11, v9, s53
	v_add3_u32 v8, v10, v8, s53
	v_lshrrev_b32_e32 v8, 16, v8
	v_lshrrev_b32_e32 v9, 16, v9
	v_lshrrev_b32_e32 v4, 16, v4
	v_lshrrev_b32_e32 v5, 16, v5
	v_and_or_b32 v5, v7, s77, v5
	v_and_or_b32 v4, v6, s77, v4
	v_and_or_b32 v3, v3, s77, v9
	v_and_or_b32 v2, v2, s77, v8
	v_add_co_u32_e32 v10, vcc, s0, v114
	ds_read_b128 v[6:9], v205 offset:2304
	s_nop 0
	v_addc_co_u32_e32 v11, vcc, 0, v115, vcc
	global_store_dwordx4 v[10:11], v[2:5], off
	ds_read_b128 v[2:5], v205 offset:2320
	v_lshlrev_b32_e32 v11, 16, v59
	v_lshlrev_b32_e32 v10, 16, v58
	s_waitcnt lgkmcnt(0)
	v_mov_b32_e32 v12, v6
	v_mov_b32_e32 v13, v8
	v_pk_mul_f32 v[10:11], v[12:13], v[10:11]
	v_and_b32_e32 v13, 0xffff0000, v59
	v_and_b32_e32 v12, 0xffff0000, v58
	v_mov_b32_e32 v8, v7
	v_pk_mul_f32 v[6:7], v[8:9], v[12:13]
	v_lshlrev_b32_e32 v9, 16, v61
	v_lshlrev_b32_e32 v8, 16, v60
	v_mov_b32_e32 v12, v2
	v_mov_b32_e32 v13, v4
	v_pk_mul_f32 v[8:9], v[12:13], v[8:9]
	v_and_b32_e32 v13, 0xffff0000, v61
	v_and_b32_e32 v12, 0xffff0000, v60
	v_mov_b32_e32 v4, v3
	v_pk_mul_f32 v[2:3], v[4:5], v[12:13]
	v_bfe_u32 v12, v7, 16, 1
	v_bfe_u32 v4, v3, 16, 1
	v_bfe_u32 v5, v2, 16, 1
	v_bfe_u32 v13, v6, 16, 1
	v_add3_u32 v6, v6, v13, s53
	v_add3_u32 v7, v7, v12, s53
	v_add3_u32 v2, v2, v5, s53
	v_add3_u32 v3, v3, v4, s53
	v_bfe_u32 v4, v10, 16, 1
	v_bfe_u32 v5, v11, 16, 1
	v_bfe_u32 v12, v8, 16, 1
	v_bfe_u32 v13, v9, 16, 1
	v_add3_u32 v9, v9, v13, s53
	v_add3_u32 v8, v8, v12, s53
	v_add3_u32 v5, v11, v5, s53
	v_add3_u32 v4, v10, v4, s53
	v_lshrrev_b32_e32 v10, 16, v4
	v_lshrrev_b32_e32 v11, 16, v5
	v_lshrrev_b32_e32 v4, 16, v8
	v_lshrrev_b32_e32 v5, 16, v9
	s_mov_b32 s0, 0xa0000
	v_and_or_b32 v5, v3, s77, v5
	v_and_or_b32 v4, v2, s77, v4
	v_and_or_b32 v3, v7, s77, v11
	v_and_or_b32 v2, v6, s77, v10
	v_add_co_u32_e32 v10, vcc, s0, v114
	ds_read_b128 v[6:9], v205 offset:4608
	s_nop 0
	v_addc_co_u32_e32 v11, vcc, 0, v115, vcc
	global_store_dwordx4 v[10:11], v[2:5], off
	ds_read_b128 v[2:5], v205 offset:4624
	v_lshlrev_b32_e32 v11, 16, v55
	v_lshlrev_b32_e32 v10, 16, v54
	s_waitcnt lgkmcnt(0)
	v_mov_b32_e32 v12, v6
	v_mov_b32_e32 v13, v8
	v_pk_mul_f32 v[10:11], v[12:13], v[10:11]
	v_and_b32_e32 v13, 0xffff0000, v55
	v_and_b32_e32 v12, 0xffff0000, v54
	v_mov_b32_e32 v8, v7
	v_pk_mul_f32 v[6:7], v[8:9], v[12:13]
	v_lshlrev_b32_e32 v9, 16, v57
	v_lshlrev_b32_e32 v8, 16, v56
	v_mov_b32_e32 v12, v2
	v_mov_b32_e32 v13, v4
	v_pk_mul_f32 v[8:9], v[12:13], v[8:9]
	v_and_b32_e32 v13, 0xffff0000, v57
	v_and_b32_e32 v12, 0xffff0000, v56
	v_mov_b32_e32 v4, v3
	v_pk_mul_f32 v[2:3], v[4:5], v[12:13]
	v_bfe_u32 v12, v7, 16, 1
	v_bfe_u32 v4, v3, 16, 1
	v_bfe_u32 v5, v2, 16, 1
	v_bfe_u32 v13, v6, 16, 1
	v_add3_u32 v6, v6, v13, s53
	v_add3_u32 v7, v7, v12, s53
	v_add3_u32 v2, v2, v5, s53
	v_add3_u32 v3, v3, v4, s53
	v_bfe_u32 v4, v10, 16, 1
	v_bfe_u32 v5, v11, 16, 1
	v_bfe_u32 v12, v8, 16, 1
	v_bfe_u32 v13, v9, 16, 1
	v_add3_u32 v9, v9, v13, s53
	v_add3_u32 v8, v8, v12, s53
	v_add3_u32 v5, v11, v5, s53
	v_add3_u32 v4, v10, v4, s53
	v_lshrrev_b32_e32 v10, 16, v4
	v_lshrrev_b32_e32 v11, 16, v5
	v_lshrrev_b32_e32 v4, 16, v8
	v_lshrrev_b32_e32 v5, 16, v9
	s_mov_b32 s0, 0xc0000
	v_and_or_b32 v5, v3, s77, v5
	v_and_or_b32 v4, v2, s77, v4
	v_and_or_b32 v3, v7, s77, v11
	v_and_or_b32 v2, v6, s77, v10
	v_add_co_u32_e32 v10, vcc, s0, v114
	ds_read_b128 v[6:9], v205 offset:6912
	s_nop 0
	v_addc_co_u32_e32 v11, vcc, 0, v115, vcc
	global_store_dwordx4 v[10:11], v[2:5], off
	ds_read_b128 v[2:5], v205 offset:6928
	v_lshlrev_b32_e32 v11, 16, v51
	v_lshlrev_b32_e32 v10, 16, v50
	s_waitcnt lgkmcnt(0)
	v_mov_b32_e32 v12, v6
	v_mov_b32_e32 v13, v8
	v_pk_mul_f32 v[10:11], v[12:13], v[10:11]
	v_and_b32_e32 v13, 0xffff0000, v51
	v_and_b32_e32 v12, 0xffff0000, v50
	v_mov_b32_e32 v8, v7
	v_pk_mul_f32 v[6:7], v[8:9], v[12:13]
	v_lshlrev_b32_e32 v9, 16, v53
	v_lshlrev_b32_e32 v8, 16, v52
	v_mov_b32_e32 v12, v2
	v_mov_b32_e32 v13, v4
	v_pk_mul_f32 v[8:9], v[12:13], v[8:9]
	v_and_b32_e32 v13, 0xffff0000, v53
	v_and_b32_e32 v12, 0xffff0000, v52
	v_mov_b32_e32 v4, v3
	v_pk_mul_f32 v[2:3], v[4:5], v[12:13]
	v_bfe_u32 v12, v7, 16, 1
	v_bfe_u32 v4, v3, 16, 1
	v_bfe_u32 v5, v2, 16, 1
	v_bfe_u32 v13, v6, 16, 1
	v_add3_u32 v7, v7, v12, s53
	v_add3_u32 v3, v3, v4, s53
	v_bfe_u32 v4, v10, 16, 1
	v_bfe_u32 v12, v8, 16, 1
	v_add3_u32 v6, v6, v13, s53
	v_add3_u32 v2, v2, v5, s53
	v_bfe_u32 v5, v11, 16, 1
	v_bfe_u32 v13, v9, 16, 1
	v_add3_u32 v8, v8, v12, s53
	v_add3_u32 v4, v10, v4, s53
	v_add3_u32 v9, v9, v13, s53
	v_add3_u32 v5, v11, v5, s53
	v_lshrrev_b32_e32 v10, 16, v4
	v_lshrrev_b32_e32 v4, 16, v8
	s_mov_b32 s0, 0xe0000
	v_lshrrev_b32_e32 v11, 16, v5
	v_lshrrev_b32_e32 v5, 16, v9
	v_and_or_b32 v4, v2, s77, v4
	v_and_or_b32 v2, v6, s77, v10
	v_add_co_u32_e32 v6, vcc, s0, v114
	s_add_u32 s0, s78, s8
	v_and_or_b32 v5, v3, s77, v5
	v_and_or_b32 v3, v7, s77, v11
	v_addc_co_u32_e32 v7, vcc, 0, v115, vcc
	s_addc_u32 s1, s79, s9
	global_store_dwordx4 v[6:7], v[2:5], off
	s_add_u32 s0, s0, s10
	s_waitcnt lgkmcnt(0)
	s_addc_u32 s1, s1, s11
	s_add_u32 s8, s0, 0x20000
	s_nop 4
	global_load_dwordx4 v[78:81], v130, s[0:1]
	s_addc_u32 s9, s1, 0
	s_nop 4
	global_load_dwordx4 v[74:77], v130, s[8:9]
	s_add_u32 s8, s0, 0x40000
	s_addc_u32 s9, s1, 0
	s_nop 4
	global_load_dwordx4 v[70:73], v130, s[8:9]
	s_add_u32 s8, s0, 0x60000
	s_addc_u32 s9, s1, 0
	s_nop 4
	global_load_dwordx4 v[66:69], v130, s[8:9]
	s_add_u32 s8, s0, 0x80000
	s_addc_u32 s9, s1, 0
	s_nop 4
	global_load_dwordx4 v[62:65], v130, s[8:9]
	s_add_u32 s8, s0, 0xa0000
	s_addc_u32 s9, s1, 0
	s_nop 4
	global_load_dwordx4 v[58:61], v130, s[8:9]
	s_add_u32 s8, s0, 0xc0000
	s_addc_u32 s9, s1, 0
	s_nop 4
	global_load_dwordx4 v[54:57], v130, s[8:9]
	s_add_u32 s0, s0, 0xe0000
	s_addc_u32 s1, s1, 0
	s_nop 4
	global_load_dwordx4 v[50:53], v130, s[0:1]
	s_add_i32 s17, s17, s14
	s_add_i32 s16, s16, s15
	s_and_b64 vcc, exec, s[6:7]
	s_barrier
	s_cbranch_vccz .LBB0_634
	s_mov_b32 s10, s19
	s_branch .LBB0_625
